# static s_setprio 1 for waves 4-7 during the P2 phase (attention and RG-LRU loops), reset to 0 at P2 exit; GEMM per-segment priority flips unchanged
# speedup vs baseline: 1.0041x; 1.0041x over previous
.LBB0_429:
	v_readlane_b32 s2, v249, 21
	v_readlane_b32 s3, v249, 22
	s_cmp_lt_i32 s2, 3
	s_cselect_b64 s[2:3], -1, 0
	s_and_b64 s[0:1], s[2:3], s[0:1]
	s_andn2_b64 vcc, exec, s[0:1]
	s_cbranch_vccnz .LBB0_550
	v_writelane_b32 v249, s2, 41
	v_readfirstlane_b32 s0, v188
	s_cmp_lt_u32 s0, 256
	s_cbranch_scc1 .Lp2prio_skip
	s_setprio 1
.Lp2prio_skip:
	v_and_b32_e32 v2, 63, v188
	v_writelane_b32 v249, s3, 42
	s_lshr_b32 s2, s0, 6
	s_mul_i32 s0, s2, 0x500
	s_add_i32 s0, s0, 0
	v_lshl_add_u32 v0, v2, 2, s0
	s_mulk_i32 s2, 0x101
	v_add_u32_e32 v3, 0x20000, v0
	s_mov_b64 s[0:1], 0
	v_mov_b32_e32 v1, 0
	s_movk_i32 s3, 0xff

.LBB0_550:
	s_setprio 0
	v_readlane_b32 s88, v249, 21
	v_readlane_b32 s89, v249, 22
	s_cmp_gt_i32 s89, 3
	s_cselect_b64 s[0:1], -1, 0
	s_and_b64 s[2:3], s[2:3], s[0:1]
	s_andn2_b64 vcc, exec, s[2:3]
	s_cbranch_vccnz .LBB0_600
	s_waitcnt vmcnt(0)
	v_cmp_eq_u32_e32 vcc, 0, v188
	s_waitcnt vmcnt(0) lgkmcnt(0)
	s_barrier
	s_and_saveexec_b64 s[2:3], vcc
	s_cbranch_execz .LBB0_599
	s_add_i32 s4, 0, 0x23fe0
	v_mov_b32_e32 v0, s4
	s_waitcnt vmcnt(0) expcnt(0) lgkmcnt(0)
	ds_read_b32 v2, v0
	s_add_i32 s4, 0, 0x23fe4
	v_mov_b32_e32 v0, s4
	ds_read_b32 v0, v0
	s_waitcnt lgkmcnt(1)
	v_cmp_ne_u32_e32 vcc, 0, v2
	s_cbranch_vccnz .LBB0_567
	v_readlane_b32 s4, v249, 17
	s_mul_i32 s24, s97, s4
	s_add_u32 s4, s30, 0x310200
	s_addc_u32 s5, s31, 0
	s_add_u32 s6, s30, 0x310400
	s_addc_u32 s7, s31, 0
	s_add_u32 s8, s30, 0x310500
	s_addc_u32 s9, s31, 0
	s_add_u32 s10, s30, 0x310600
	s_addc_u32 s11, s31, 0
	s_add_u32 s12, s30, 0x310700
	s_addc_u32 s13, s31, 0
	s_add_u32 s14, s30, 0x310800
	s_addc_u32 s15, s31, 0
	s_add_u32 s16, s30, 0x310900
	s_addc_u32 s17, s31, 0
	s_add_u32 s18, s30, 0x310a00
	s_addc_u32 s19, s31, 0
	s_add_u32 s20, s30, 0x310b00
	s_addc_u32 s21, s31, 0
	s_add_u32 s22, s30, 0x310c00
	s_addc_u32 s23, s31, 0
	s_add_u32 s34, s30, 0x310d00
	s_addc_u32 s35, s31, 0
	s_add_u32 s56, s30, 0x310e00
	s_addc_u32 s57, s31, 0
	s_add_u32 s58, s30, 0x310f00
	s_addc_u32 s59, s31, 0
	s_add_u32 s60, s30, 0x311000
	s_addc_u32 s61, s31, 0
	s_add_u32 s62, s30, 0x311100
	s_addc_u32 s63, s31, 0
	s_add_u32 s68, s30, 0x311200
	s_addc_u32 s69, s31, 0
	s_add_u32 s70, s30, 0x311300
	s_mul_i32 s24, s24, s96
	s_addc_u32 s71, s31, 0
	s_mov_b32 s25, 1
	v_mov_b32_e32 v16, 0
	s_branch .LBB0_555
